# GLA: q/k/v/lr register prefetch moved a full chunk ahead (rv and rq issued at previous chunk end), vf fragments relocated
# baseline (speedup 1.0000x reference)
; __device__ __forceinline__ unsigned cvt_pk_bf16(float lo, float hi) { const f32x2 v = {lo, hi}; const bf16x2_t b = __builtin_convertvector(v, bf16x2_t); return __builtin_bit_cast(unsigned, b); }
; __device__ __forceinline__ float bflo(unsigned w) { return __uint_as_float(w << 16); }
; __device__ __forceinline__ float bfhi(unsigned w) { return __uint_as_float(w & 0xffff0000u); }
; template <bool PASS2>
; __device__ __forceinline__ void gla_pass(LAS unsigned char* lds, const Params& p, int layer) {
;     ...
;             { const float* Wc = (dir ? p.wdu_b : p.wdu_f) + (size_t)layer * 16 * 512 + h * 128 + wid * 16 + fr;
;               float wv[8]; unsigned h1[4], h2[4];
; #pragma unroll
;               for (int j = 0; j < 8; ++j) wv[j] = Wc[((fq & 1) * 8 + j) * 512];
; #pragma unroll
;               for (int jp = 0; jp < 4; ++jp) { const float a = wv[2 * jp], bq = wv[2 * jp + 1]; const unsigned hi = cvt_pk_bf16(a, bq);
;                   const unsigned lo = cvt_pk_bf16(a - bflo(hi), bq - bfhi(hi)); h1[jp] = hi; h2[jp] = fq < 2 ? lo : 0u; }
;               wB1 = __builtin_bit_cast(bf16x8, (u32x4){h1[0], h1[1], h1[2], h1[3]}); wB2 = __builtin_bit_cast(bf16x8, (u32x4){h2[0], h2[1], h2[2], h2[3]});
;               biasx = (dir ? p.bd_b : p.bd_f)[layer * 512 + h * 128 + wid * 16 + fr]; }
;             f32x4 accS[8][2];
; #pragma unroll
;             for (int m8 = 0; m8 < 8; ++m8)
; #pragma unroll
;                 for (int n = 0; n < 2; ++n) accS[m8][n] = (f32x4){0.f, 0.f, 0.f, 0.f};
;             float gtot0 = 0.f, gtot1 = 0.f;
;             u32x4 rk[2], rq[2], rv[4]; u32x4 rl = (u32x4){0u, 0u, 0u, 0u};
;     ...
;             GLA_ISSUE(0);
;     ...
;                 for (int it = 0; it < 4; ++it) { const int pi = tid + 512 * it, row = pi >> 5, seg = pi & 31;
;                     rv[it] = *(const u32x4*)(P + (size_t)(t0 + row) * PW + 1024 + h * 256 + seg * 8); }
.LBB0_446:
	s_and_b64 s[4:5], s[14:15], exec
	s_cselect_b32 s4, 24, 40
	v_readlane_b32 s34, v254, 23
	v_readlane_b32 s35, v254, 24
	s_add_u32 s4, s34, s4
	s_addc_u32 s5, s35, 0
	s_load_dwordx2 s[4:5], s[4:5], 0x0
	v_mov_b32_e32 v135, v147
	s_waitcnt lgkmcnt(0)
	s_add_u32 s4, s4, s88
	s_addc_u32 s5, s5, s89
	s_add_u32 s4, s4, s94
	s_addc_u32 s5, s5, 0
	s_add_u32 s4, s4, s76
	s_addc_u32 s5, s5, s77
	v_lshl_add_u64 v[0:1], s[4:5], 0, v[146:147]
	v_lshl_add_u64 v[0:1], v[0:1], 0, v[134:135]
	s_movk_i32 s4, 0x1000
	v_add_co_u32_e32 v2, vcc, s4, v0
	s_movk_i32 s4, 0x2000
	s_nop 0
	v_addc_co_u32_e32 v3, vcc, 0, v1, vcc
	v_add_co_u32_e32 v4, vcc, s4, v0
	s_movk_i32 s4, 0x3000
	s_nop 0
	v_addc_co_u32_e32 v5, vcc, 0, v1, vcc
	global_load_dword v14, v[4:5], off offset:-4096
	global_load_dword v18, v[4:5], off
	global_load_dword v19, v[4:5], off offset:2048
	v_add_co_u32_e32 v4, vcc, s4, v0
	s_and_b64 s[4:5], s[14:15], exec
	s_cselect_b32 s4, 32, 48
	s_add_u32 s4, s34, s4
	s_addc_u32 s5, s35, 0
	s_load_dwordx2 s[4:5], s[4:5], 0x0
	v_addc_co_u32_e32 v5, vcc, 0, v1, vcc
	global_load_dword v16, v[0:1], off
	global_load_dword v17, v[0:1], off offset:2048
	global_load_dword v15, v[2:3], off offset:2048
	global_load_dword v20, v[4:5], off
	global_load_dword v21, v[4:5], off offset:2048
	s_waitcnt lgkmcnt(0)
	v_lshl_add_u64 v[0:1], v[138:139], 2, s[4:5]
	s_and_b64 s[4:5], s[14:15], exec
	s_cselect_b32 s4, 0, 0x1c0
	s_or_b32 s34, s4, s97
	global_load_dword v135, v[0:1], off
	v_add_u32_e32 v0, s34, v189
	v_add_u32_e32 v2, s34, v190
	v_mad_i64_i32 v[0:1], s[4:5], v0, s80, v[140:141]
	v_mad_i64_i32 v[4:5], s[4:5], v2, s80, v[140:141]
	global_load_dwordx4 v[104:107], v[0:1], off
	global_load_dwordx4 v[0:3], v[0:1], off offset:1024
	s_nop 0
	global_load_dwordx4 v[100:103], v[4:5], off
	global_load_dwordx4 v[4:7], v[4:5], off offset:1024
	v_add_u32_e32 v84, s34, v193
	v_add_u32_e32 v86, s34, v194
	v_add_u32_e32 v92, s34, v195
	v_add_u32_e32 v94, s34, v196
	v_mad_i64_i32 v[84:85], s[4:5], v84, s80, v[160:161]
	v_mad_i64_i32 v[88:89], s[4:5], v86, s80, v[160:161]
	v_mad_i64_i32 v[92:93], s[4:5], v92, s80, v[160:161]
	v_mad_i64_i32 v[96:97], s[4:5], v94, s80, v[160:161]
	global_load_dwordx4 v[84:87], v[84:85], off offset:2048
	s_nop 0
	global_load_dwordx4 v[88:91], v[88:89], off offset:2048
	s_nop 0
	global_load_dwordx4 v[92:95], v[92:93], off offset:2048
	s_nop 0
	global_load_dwordx4 v[96:99], v[96:97], off offset:2048
	s_mov_b64 s[4:5], exec
	v_readlane_b32 s36, v254, 37
	v_readlane_b32 s37, v254, 38
	s_and_b64 s[36:37], s[4:5], s[36:37]
	s_xor_b64 s[4:5], s[36:37], s[4:5]
	s_mov_b64 exec, s[36:37]
	s_lshl_b32 s0, s95, 5
	s_or_saveexec_b64 s[4:5], s[4:5]
	v_mov_b32_e32 v8, v147
	v_mov_b32_e32 v9, v147
	v_mov_b32_e32 v10, v147
	v_mov_b32_e32 v11, v147
	v_mov_b64_e32 v[22:23], s[0:1]
	s_xor_b64 exec, exec, s[4:5]
	s_cbranch_execz .LBB0_450
	v_add_u32_e32 v8, s34, v188
	v_ashrrev_i32_e32 v9, 31, v8
	v_readlane_b32 s34, v254, 39
	v_lshlrev_b64 v[8:9], 7, v[8:9]
	v_readlane_b32 s35, v254, 40
	v_lshlrev_b32_e32 v10, 1, v124
	v_mov_b32_e32 v11, v147
	v_lshl_add_u64 v[8:9], s[34:35], 0, v[8:9]
	s_lshl_b32 s34, s95, 6
	s_mov_b32 s35, s1
	v_lshl_add_u64 v[8:9], v[8:9], 0, s[34:35]
	v_lshl_add_u64 v[8:9], v[8:9], 0, v[10:11]
	global_load_dwordx4 v[8:11], v[8:9], off
	s_mov_b32 s37, s1
	s_lshl_b32 s36, s95, 5
	v_mov_b64_e32 v[22:23], s[36:37]

; #define LAS __attribute__((address_space(3)))
; #define MFMA16(a, b, c) __builtin_amdgcn_mfma_f32_16x16x32_bf16((a), (b), (c), 0, 0, 0)
; template <bool PASS2>
; __device__ __forceinline__ void gla_pass(LAS unsigned char* lds, const Params& p, int layer) {
;     ...
;                 for (int m8 = 0; m8 < 8; ++m8) { const f32x4 d = *(LAS f32x4*)(lds + SDEC + (m8 * 16 + 4 * fq) * 4);
; #pragma unroll
;                     for (int kb2 = 0; kb2 < 2; ++kb2) {
;                         const int a0 = SK + (kb2 * 32 + fq * 8 + (fr >> 2)) * 272 + (m8 * 16 + 4 * (fr & 3)) * 2;
;                         const s16x4 lo = __builtin_amdgcn_ds_read_tr16_b64_v4i16((LAS s16x4*)(lds + a0));
;                         const s16x4 hi = __builtin_amdgcn_ds_read_tr16_b64_v4i16((LAS s16x4*)(lds + a0 + 4 * 272));
;                         const bf16x8 A = __builtin_shufflevector(lo, hi, 0, 1, 2, 3, 4, 5, 6, 7);
; #pragma unroll
;                         for (int n = 0; n < 2; ++n) accS[m8][n] = MFMA16(A, vf[n][kb2], accS[m8][n]); }
; #pragma unroll
;                     for (int n = 0; n < 2; ++n) accS[m8][n] = accS[m8][n] * d; }
.LBB0_452:
	v_add_u32_e32 v152, 0x14c00, v206
	v_add_u32_e32 v153, v207, v124
	s_mov_b32 s70, s0
	ds_read_b64_tr_b16 v[108:109], v153 offset:17408
	ds_read_b64_tr_b16 v[110:111], v153 offset:18496
	ds_read_b64_tr_b16 v[112:113], v233 offset:17408
	ds_read_b64_tr_b16 v[114:115], v233 offset:18496
	ds_read_b128 v[244:247], v152
	ds_read_b64_tr_b16 v[166:167], v153 offset:17440
	ds_read_b64_tr_b16 v[168:169], v153 offset:18528
	ds_read_b64_tr_b16 v[170:171], v233 offset:17440
	ds_read_b64_tr_b16 v[172:173], v233 offset:18528
	ds_read_b128 v[250:253], v152 offset:64
	v_add_f32_e32 v163, v163, v174
	v_add_f32_e32 v162, v162, v137
	s_cmp_eq_u32 s68, 8
	s_waitcnt lgkmcnt(5)
	v_mfma_f32_16x16x32_bf16 v[64:67], v[108:111], v[176:179], v[64:67]
	v_mfma_f32_16x16x32_bf16 v[52:55], v[108:111], v[236:239], v[52:55]
	v_mfma_f32_16x16x32_bf16 v[64:67], v[112:115], v[180:183], v[64:67]
	v_mfma_f32_16x16x32_bf16 v[52:55], v[112:115], v[240:243], v[52:55]
	ds_read_b64_tr_b16 v[108:109], v153 offset:17472
	ds_read_b64_tr_b16 v[110:111], v153 offset:18560
	ds_read_b64_tr_b16 v[112:113], v233 offset:17472
	ds_read_b64_tr_b16 v[114:115], v233 offset:18560
	s_nop 3
	v_pk_mul_f32 v[64:65], v[244:245], v[64:65]
	v_pk_mul_f32 v[66:67], v[246:247], v[66:67]
	v_pk_mul_f32 v[52:53], v[244:245], v[52:53]
	v_pk_mul_f32 v[54:55], v[246:247], v[54:55]
	ds_read_b128 v[244:247], v152 offset:128
	s_waitcnt lgkmcnt(5)
	v_mfma_f32_16x16x32_bf16 v[40:43], v[166:169], v[176:179], v[40:43]
	v_mfma_f32_16x16x32_bf16 v[20:23], v[166:169], v[236:239], v[20:23]
	v_mfma_f32_16x16x32_bf16 v[40:43], v[170:173], v[180:183], v[40:43]
	v_mfma_f32_16x16x32_bf16 v[20:23], v[170:173], v[240:243], v[20:23]
	ds_read_b64_tr_b16 v[166:167], v153 offset:17504
	ds_read_b64_tr_b16 v[168:169], v153 offset:18592
	ds_read_b64_tr_b16 v[170:171], v233 offset:17504
	ds_read_b64_tr_b16 v[172:173], v233 offset:18592
	s_nop 3
	v_pk_mul_f32 v[40:41], v[250:251], v[40:41]
	v_pk_mul_f32 v[42:43], v[252:253], v[42:43]
	v_pk_mul_f32 v[20:21], v[250:251], v[20:21]
	v_pk_mul_f32 v[22:23], v[252:253], v[22:23]
	ds_read_b128 v[250:253], v152 offset:192
	s_waitcnt lgkmcnt(5)
	v_mfma_f32_16x16x32_bf16 v[44:47], v[108:111], v[176:179], v[44:47]
	v_mfma_f32_16x16x32_bf16 v[48:51], v[108:111], v[236:239], v[48:51]
	v_mfma_f32_16x16x32_bf16 v[44:47], v[112:115], v[180:183], v[44:47]
	v_mfma_f32_16x16x32_bf16 v[48:51], v[112:115], v[240:243], v[48:51]
	ds_read_b64_tr_b16 v[108:109], v153 offset:17536
	ds_read_b64_tr_b16 v[110:111], v153 offset:18624
	ds_read_b64_tr_b16 v[112:113], v233 offset:17536
	ds_read_b64_tr_b16 v[114:115], v233 offset:18624
	s_nop 3
	v_pk_mul_f32 v[44:45], v[244:245], v[44:45]
	v_pk_mul_f32 v[46:47], v[246:247], v[46:47]
	v_pk_mul_f32 v[48:49], v[244:245], v[48:49]
	v_pk_mul_f32 v[50:51], v[246:247], v[50:51]
	ds_read_b128 v[244:247], v152 offset:256
	s_waitcnt lgkmcnt(5)
	v_mfma_f32_16x16x32_bf16 v[68:71], v[166:169], v[176:179], v[68:71]
	v_mfma_f32_16x16x32_bf16 v[72:75], v[166:169], v[236:239], v[72:75]
	v_mfma_f32_16x16x32_bf16 v[68:71], v[170:173], v[180:183], v[68:71]
	v_mfma_f32_16x16x32_bf16 v[72:75], v[170:173], v[240:243], v[72:75]
	ds_read_b64_tr_b16 v[166:167], v153 offset:17568
	ds_read_b64_tr_b16 v[168:169], v153 offset:18656
	ds_read_b64_tr_b16 v[170:171], v233 offset:17568
	ds_read_b64_tr_b16 v[172:173], v233 offset:18656
	s_nop 3
	v_pk_mul_f32 v[68:69], v[250:251], v[68:69]
	v_pk_mul_f32 v[70:71], v[252:253], v[70:71]
	v_pk_mul_f32 v[72:73], v[250:251], v[72:73]
	v_pk_mul_f32 v[74:75], v[252:253], v[74:75]
	ds_read_b128 v[250:253], v152 offset:320
	s_waitcnt lgkmcnt(5)
	v_mfma_f32_16x16x32_bf16 v[56:59], v[108:111], v[176:179], v[56:59]
	v_mfma_f32_16x16x32_bf16 v[60:63], v[108:111], v[236:239], v[60:63]
	v_mfma_f32_16x16x32_bf16 v[56:59], v[112:115], v[180:183], v[56:59]
	v_mfma_f32_16x16x32_bf16 v[60:63], v[112:115], v[240:243], v[60:63]
	ds_read_b64_tr_b16 v[108:109], v153 offset:17600
	ds_read_b64_tr_b16 v[110:111], v153 offset:18688
	ds_read_b64_tr_b16 v[112:113], v233 offset:17600
	ds_read_b64_tr_b16 v[114:115], v233 offset:18688
	s_nop 3
	v_pk_mul_f32 v[56:57], v[244:245], v[56:57]
	v_pk_mul_f32 v[58:59], v[246:247], v[58:59]
	v_pk_mul_f32 v[60:61], v[244:245], v[60:61]
	v_pk_mul_f32 v[62:63], v[246:247], v[62:63]
	ds_read_b128 v[244:247], v152 offset:384
	s_waitcnt lgkmcnt(5)
	v_mfma_f32_16x16x32_bf16 v[32:35], v[166:169], v[176:179], v[32:35]
	v_mfma_f32_16x16x32_bf16 v[36:39], v[166:169], v[236:239], v[36:39]
	v_mfma_f32_16x16x32_bf16 v[32:35], v[170:173], v[180:183], v[32:35]
	v_mfma_f32_16x16x32_bf16 v[36:39], v[170:173], v[240:243], v[36:39]
	ds_read_b64_tr_b16 v[166:167], v153 offset:17632
	ds_read_b64_tr_b16 v[168:169], v153 offset:18720
	ds_read_b64_tr_b16 v[170:171], v233 offset:17632
	ds_read_b64_tr_b16 v[172:173], v233 offset:18720
	s_nop 3
	v_pk_mul_f32 v[32:33], v[250:251], v[32:33]
	v_pk_mul_f32 v[34:35], v[252:253], v[34:35]
	v_pk_mul_f32 v[36:37], v[250:251], v[36:37]
	v_pk_mul_f32 v[38:39], v[252:253], v[38:39]
	ds_read_b128 v[250:253], v152 offset:448
	s_waitcnt lgkmcnt(5)
	v_mfma_f32_16x16x32_bf16 v[24:27], v[108:111], v[176:179], v[24:27]
	v_mfma_f32_16x16x32_bf16 v[28:31], v[108:111], v[236:239], v[28:31]
	v_mfma_f32_16x16x32_bf16 v[24:27], v[112:115], v[180:183], v[24:27]
	v_mfma_f32_16x16x32_bf16 v[28:31], v[112:115], v[240:243], v[28:31]
	s_nop 7
	v_pk_mul_f32 v[24:25], v[244:245], v[24:25]
	v_pk_mul_f32 v[26:27], v[246:247], v[26:27]
	v_pk_mul_f32 v[28:29], v[244:245], v[28:29]
	v_pk_mul_f32 v[30:31], v[246:247], v[30:31]
	s_waitcnt lgkmcnt(0)
	s_barrier
	v_mfma_f32_16x16x32_bf16 v[76:79], v[166:169], v[176:179], v[76:79]
	v_mfma_f32_16x16x32_bf16 v[80:83], v[166:169], v[236:239], v[80:83]
	v_mfma_f32_16x16x32_bf16 v[76:79], v[170:173], v[180:183], v[76:79]
	v_mfma_f32_16x16x32_bf16 v[80:83], v[170:173], v[240:243], v[80:83]
	s_nop 7
	v_pk_mul_f32 v[76:77], v[250:251], v[76:77]
	v_pk_mul_f32 v[78:79], v[252:253], v[78:79]
	v_pk_mul_f32 v[80:81], v[250:251], v[80:81]
	v_pk_mul_f32 v[82:83], v[252:253], v[82:83]
	s_cbranch_scc1 .LBB0_515
; #define LAS __attribute__((address_space(3)))
; template <bool PASS2>
; __device__ __forceinline__ void gla_pass(LAS unsigned char* lds, const Params& p, int layer) {
;     ...
;             for (int cc = 0; cc < 8; ++cc) {
;                 const int chunk = dir ? 7 - cc : cc;
;                 const int t0 = b * SEQL + grp * 512 + chunk * 64;
; #pragma unroll
;                 for (int it = 0; it < 2; ++it) { const int pi = tid + 512 * it, row = pi >> 4, seg = pi & 15;
;                     *(LAS u32x4*)(lds + SK + row * 272 + seg * 16) = rk[it];
;                     if (PASS2) rq[it] = *(const u32x4*)(P + (size_t)(t0 + row) * PW + h * 128 + seg * 8); }
; #pragma unroll
;                 for (int it = 0; it < 4; ++it) { const int pi = tid + 512 * it, row = pi >> 5, seg = pi & 31;
;                     rv[it] = *(const u32x4*)(P + (size_t)(t0 + row) * PW + 1024 + h * 256 + seg * 8); }
;                 if (tid < 256) { const int row = tid >> 2, seg = tid & 3; *(LAS u32x4*)(lds + SLR + row * 64 + seg * 16) = rl; }
.LBB0_453:
	s_sub_i32 s66, 7, s68
	s_and_b64 s[4:5], s[14:15], exec
	s_cselect_b32 s4, s68, s66
	s_lshl_b32 s69, s4, 6
	s_add_i32 s69, s69, s97
	v_add_u32_e32 v108, v184, v191
	s_waitcnt vmcnt(6)
	ds_write_b128 v108, v[0:3] offset:17408
	v_add_u32_e32 v108, v184, v192
	s_waitcnt vmcnt(6)
	ds_write_b128 v108, v[4:7] offset:17408
	s_and_saveexec_b64 s[4:5], s[12:13]
	ds_write_b128 v211, v[8:11]
	s_or_b64 exec, exec, s[4:5]
	s_sub_i32 s66, 6, s68
	s_add_i32 s4, s68, 1
	s_and_b64 vcc, s[14:15], exec
	s_cselect_b32 s4, s4, s66
	s_lshl_b32 s66, s4, 6
	s_add_i32 s66, s66, s97
	v_add_u32_e32 v0, s66, v189
	v_add_u32_e32 v2, s66, v190
	v_mad_i64_i32 v[0:1], s[4:5], v0, s80, v[140:141]
	v_mad_i64_i32 v[4:5], s[4:5], v2, s80, v[140:141]
	global_load_dwordx4 v[0:3], v[0:1], off offset:1024
	s_nop 0
	global_load_dwordx4 v[4:7], v[4:5], off offset:1024
	s_and_saveexec_b64 s[4:5], s[12:13]
	s_cbranch_execz .Lgla_t3_skip
	v_add_u32_e32 v8, s66, v188
	v_ashrrev_i32_e32 v9, 31, v8
	v_lshlrev_b64 v[8:9], 7, v[8:9]
	v_lshl_add_u64 v[8:9], v[164:165], 0, v[8:9]
	global_load_dwordx4 v[8:11], v[8:9], off

; template <bool PASS2>
; __device__ __forceinline__ void gla_pass(LAS unsigned char* lds, const Params& p, int layer) {
;     ...
;                     f32x4 accP[2];
; #pragma unroll
;                     for (int s = 0; s < 2; ++s) { const int tt = wid * 2 + s, ib = tt >> 2, jb = tt & 3; f32x4 a = (f32x4){0.f, 0.f, 0.f, 0.f};
; #pragma unroll
;                         for (int kb = 0; kb < 4; ++kb) { const bf16x8 A = *(LAS bf16x8*)(lds + SK + (jb * 16 + fr) * 272 + (kb * 32 + fq * 8) * 2);
;                             const bf16x8 B = *(LAS bf16x8*)(lds + SQ + (ib * 16 + fr) * 272 + (kb * 32 + fq * 8) * 2); a = MFMA16(A, B, a); }
;                         accP[s] = a; }
; #pragma unroll
;                     for (int s = 0; s < 2; ++s) { const int tt = wid * 2 + s, ib = tt >> 2, jb = tt & 3; const int i = ib * 16 + fr, jbase = jb * 16 + 4 * fq; float v[4];
; #pragma unroll
;                         for (int jj = 0; jj < 4; ++jj) { const int j = jbase + jj; const bool keep = dir == 0 ? (j <= i) : (j > i); v[jj] = keep ? accP[s][jj] : 0.f; }
;                         *(LAS u32x2*)(lds + SP + i * 144 + jbase * 2) = (u32x2){cvt_pk_bf16(v[0], v[1]), cvt_pk_bf16(v[2], v[3])}; }
; #pragma unroll
;                     for (int m8 = 0; m8 < 8; ++m8)
; #pragma unroll
;                         for (int n = 0; n < 2; ++n) { const f32x4 sv = accS[m8][n];
;                             *(LAS u32x2*)(lds + SST + (wid * 32 + n * 16 + fr) * 272 + (m8 * 16 + 4 * fq) * 2) = (u32x2){cvt_pk_bf16(sv[0], sv[1]), cvt_pk_bf16(sv[2], sv[3])}; }
;                     __syncthreads();
;                 }
;                 bf16x8 vf[2][2];
; #pragma unroll
;                 for (int n = 0; n < 2; ++n)
; #pragma unroll
;                     for (int kb2 = 0; kb2 < 2; ++kb2) {
;                         const int a0 = SV + (kb2 * 32 + fq * 8 + (fr >> 2)) * 528 + (wid * 32 + n * 16 + 4 * (fr & 3)) * 2;
;                         const s16x4 lo = __builtin_amdgcn_ds_read_tr16_b64_v4i16((LAS s16x4*)(lds + a0));
;                         const s16x4 hi = __builtin_amdgcn_ds_read_tr16_b64_v4i16((LAS s16x4*)(lds + a0 + 4 * 528));
;                         vf[n][kb2] = __builtin_shufflevector(lo, hi, 0, 1, 2, 3, 4, 5, 6, 7); }
;                 if (PASS2) {
; #pragma unroll
;                     for (int n = 0; n < 2; ++n) {
;                         f32x4 accO[4];
; #pragma unroll
.Lgla_opf_skip:
	s_waitcnt lgkmcnt(0)
	s_barrier
	ds_read_b128 v[84:87], v216 offset:17408
	ds_read_b128 v[88:91], v217
	ds_read_b128 v[92:95], v216 offset:17472
	s_waitcnt lgkmcnt(1)
	v_mfma_f32_16x16x32_bf16 v[84:87], v[84:87], v[88:91], 0
	ds_read_b128 v[96:99], v217 offset:64
	ds_read_b128 v[100:103], v216 offset:17536
	v_add_u32_e32 v152, v205, v124
	s_and_b64 vcc, exec, s[66:67]
	s_waitcnt lgkmcnt(1)
	v_mfma_f32_16x16x32_bf16 v[84:87], v[92:95], v[96:99], v[84:87]
	ds_read_b128 v[92:95], v217 offset:128
	ds_read_b128 v[104:107], v218 offset:17408
	s_waitcnt lgkmcnt(1)
	v_mfma_f32_16x16x32_bf16 v[84:87], v[100:103], v[92:95], v[84:87]
	ds_read_b128 v[100:103], v216 offset:17600
	ds_read_b128 v[108:111], v217 offset:192
	s_waitcnt lgkmcnt(2)
	v_mfma_f32_16x16x32_bf16 v[88:91], v[104:107], v[88:91], 0
	ds_read_b128 v[104:107], v218 offset:17472
	s_waitcnt lgkmcnt(1)
	v_mfma_f32_16x16x32_bf16 v[84:87], v[100:103], v[108:111], v[84:87]
	ds_read_b128 v[100:103], v218 offset:17536
	s_waitcnt lgkmcnt(1)
	v_mfma_f32_16x16x32_bf16 v[88:91], v[104:107], v[96:99], v[88:91]
	ds_read_b128 v[96:99], v218 offset:17600
	s_nop 3
	v_cndmask_b32_e64 v104, 0, v84, s[50:51]
	s_waitcnt lgkmcnt(1)
	v_mfma_f32_16x16x32_bf16 v[88:91], v[100:103], v[92:95], v[88:91]
	v_cndmask_b32_e64 v92, 0, v85, s[52:53]
	v_cndmask_b32_e64 v93, 0, v86, s[54:55]
	v_cndmask_b32_e64 v94, 0, v87, s[56:57]
	s_waitcnt lgkmcnt(0)
	v_mfma_f32_16x16x32_bf16 v[84:87], v[96:99], v[108:111], v[88:91]
	s_nop 2
	v_cvt_pk_bf16_f32 v88, v104, v92
	s_nop 3
	v_cndmask_b32_e64 v84, 0, v84, s[58:59]
	v_cndmask_b32_e64 v85, 0, v85, s[60:61]
	v_cndmask_b32_e64 v86, 0, v86, s[62:63]
	v_cndmask_b32_e64 v87, 0, v87, s[64:65]
	v_cvt_pk_bf16_f32 v89, v93, v94
	v_cvt_pk_bf16_f32 v84, v84, v85
	v_cvt_pk_bf16_f32 v85, v86, v87
	ds_write_b64 v219, v[88:89]
	ds_write_b64 v227, v[84:85]
	v_cvt_pk_bf16_f32 v84, v64, v65
	v_cvt_pk_bf16_f32 v85, v66, v67
	v_cvt_pk_bf16_f32 v88, v40, v41
	v_cvt_pk_bf16_f32 v89, v42, v43
	v_cvt_pk_bf16_f32 v86, v52, v53
	v_cvt_pk_bf16_f32 v87, v54, v55
	ds_write2_b64 v228, v[84:85], v[88:89] offset1:4
	v_cvt_pk_bf16_f32 v84, v20, v21
	v_cvt_pk_bf16_f32 v85, v22, v23
	v_add_u32_e32 v90, 0x1000, v228
	ds_write2_b64 v90, v[86:87], v[84:85] offset0:32 offset1:36
	v_cvt_pk_bf16_f32 v84, v44, v45
	v_cvt_pk_bf16_f32 v85, v46, v47
	v_cvt_pk_bf16_f32 v88, v68, v69
	v_cvt_pk_bf16_f32 v89, v70, v71
	v_cvt_pk_bf16_f32 v86, v48, v49
	v_cvt_pk_bf16_f32 v87, v50, v51
	ds_write2_b64 v228, v[84:85], v[88:89] offset0:8 offset1:12
	v_cvt_pk_bf16_f32 v84, v72, v73
	v_cvt_pk_bf16_f32 v85, v74, v75
	ds_write2_b64 v90, v[86:87], v[84:85] offset0:40 offset1:44
	v_cvt_pk_bf16_f32 v84, v56, v57
	v_cvt_pk_bf16_f32 v85, v58, v59
	v_cvt_pk_bf16_f32 v88, v32, v33
	v_cvt_pk_bf16_f32 v89, v34, v35
	v_cvt_pk_bf16_f32 v86, v60, v61
	v_cvt_pk_bf16_f32 v87, v62, v63
	ds_write2_b64 v228, v[84:85], v[88:89] offset0:16 offset1:20
	v_cvt_pk_bf16_f32 v84, v36, v37
	v_cvt_pk_bf16_f32 v85, v38, v39
	ds_write2_b64 v90, v[86:87], v[84:85] offset0:48 offset1:52
	v_cvt_pk_bf16_f32 v84, v24, v25
	v_cvt_pk_bf16_f32 v85, v26, v27
	v_cvt_pk_bf16_f32 v88, v76, v77
	v_cvt_pk_bf16_f32 v89, v78, v79
	v_cvt_pk_bf16_f32 v86, v28, v29
	v_cvt_pk_bf16_f32 v87, v30, v31
	ds_write2_b64 v228, v[84:85], v[88:89] offset0:24 offset1:28
	v_cvt_pk_bf16_f32 v84, v80, v81
	v_cvt_pk_bf16_f32 v85, v82, v83
	ds_write2_b64 v90, v[86:87], v[84:85] offset0:56 offset1:60
	s_waitcnt lgkmcnt(0)
	s_barrier
	ds_read_b64_tr_b16 v[176:177], v152 offset:35840
	ds_read_b64_tr_b16 v[178:179], v152 offset:37952
	ds_read_b64_tr_b16 v[180:181], v229 offset:35840
	ds_read_b64_tr_b16 v[182:183], v229 offset:37952
	ds_read_b64_tr_b16 v[236:237], v152 offset:35872
	ds_read_b64_tr_b16 v[238:239], v152 offset:37984
	ds_read_b64_tr_b16 v[240:241], v229 offset:35872
	ds_read_b64_tr_b16 v[242:243], v229 offset:37984
	ds_read_b128 v[84:87], v230
	ds_read_b128 v[88:91], v234
	ds_read_b128 v[92:95], v234 offset:4352
	ds_read_b128 v[96:99], v234 offset:8704
	ds_read_b128 v[166:169], v234 offset:13056
	ds_read_b128 v[170:173], v230 offset:64
	s_waitcnt lgkmcnt(4)
	v_mfma_f32_16x16x32_bf16 v[100:103], v[84:87], v[88:91], 0
	ds_read_b128 v[88:91], v234 offset:64
	s_waitcnt lgkmcnt(4)
	v_mfma_f32_16x16x32_bf16 v[104:107], v[84:87], v[92:95], 0
	ds_read_b128 v[92:95], v234 offset:4416
	s_waitcnt lgkmcnt(4)
	v_mfma_f32_16x16x32_bf16 v[108:111], v[84:87], v[96:99], 0
	ds_read_b128 v[96:99], v234 offset:8768
	s_waitcnt lgkmcnt(4)
	v_mfma_f32_16x16x32_bf16 v[112:115], v[84:87], v[166:169], 0
	ds_read_b128 v[84:87], v234 offset:13120
	ds_read_b128 v[166:169], v230 offset:128
	s_waitcnt lgkmcnt(4)
	v_mfma_f32_16x16x32_bf16 v[100:103], v[170:173], v[88:91], v[100:103]
	ds_read_b128 v[88:91], v234 offset:128
	s_waitcnt lgkmcnt(4)
	v_mfma_f32_16x16x32_bf16 v[104:107], v[170:173], v[92:95], v[104:107]
	ds_read_b128 v[92:95], v234 offset:4480
	s_waitcnt lgkmcnt(4)
	v_mfma_f32_16x16x32_bf16 v[108:111], v[170:173], v[96:99], v[108:111]
	ds_read_b128 v[96:99], v234 offset:8832
	s_waitcnt lgkmcnt(4)
	v_mfma_f32_16x16x32_bf16 v[112:115], v[170:173], v[84:87], v[112:115]
	ds_read_b128 v[170:173], v234 offset:13184
	ds_read_b128 v[84:87], v230 offset:192
	s_waitcnt lgkmcnt(4)
	v_mfma_f32_16x16x32_bf16 v[100:103], v[166:169], v[88:91], v[100:103]
	ds_read_b128 v[88:91], v234 offset:192
	s_waitcnt lgkmcnt(4)
	v_mfma_f32_16x16x32_bf16 v[104:107], v[166:169], v[92:95], v[104:107]
	ds_read_b128 v[92:95], v234 offset:4544
	s_waitcnt lgkmcnt(4)
	v_mfma_f32_16x16x32_bf16 v[108:111], v[166:169], v[96:99], v[108:111]
	ds_read_b128 v[96:99], v234 offset:8896
	s_waitcnt lgkmcnt(4)
; #define LAS __attribute__((address_space(3)))
; __device__ __forceinline__ unsigned cvt_pk_bf16(float lo, float hi) { const f32x2 v = {lo, hi}; const bf16x2_t b = __builtin_convertvector(v, bf16x2_t); return __builtin_bit_cast(unsigned, b); }
; __device__ __forceinline__ float bflo(unsigned w) { return __uint_as_float(w << 16); }
; __device__ __forceinline__ float bfhi(unsigned w) { return __uint_as_float(w & 0xffff0000u); }
; #define MFMA16(a, b, c) __builtin_amdgcn_mfma_f32_16x16x32_bf16((a), (b), (c), 0, 0, 0)
; template <bool PASS2>
; __device__ __forceinline__ void gla_pass(LAS unsigned char* lds, const Params& p, int layer) {
;     ...
;                         for (int kb = 0; kb < 4; ++kb) { const bf16x8 A = *(LAS bf16x8*)(lds + SST + (wid * 32 + n * 16 + fr) * 272 + (kb * 32 + fq * 8) * 2);
; #pragma unroll
;                             for (int m = 0; m < 4; ++m) { const bf16x8 B = *(LAS bf16x8*)(lds + SQ + (m * 16 + fr) * 272 + (kb * 32 + fq * 8) * 2); accO[m] = MFMA16(A, B, accO[m]); } }
; #pragma unroll
;                         for (int kb2 = 0; kb2 < 2; ++kb2)
; #pragma unroll
;                             for (int m = 0; m < 4; ++m) { const bf16x8 B = *(LAS bf16x8*)(lds + SP + (m * 16 + fr) * 144 + (kb2 * 32 + fq * 8) * 2); accO[m] = MFMA16(vf[n][kb2], B, accO[m]); }
; #pragma unroll
;                         for (int m = 0; m < 4; ++m) { bf16_t* dst = O + (size_t)(t0 + m * 16 + fr) * 1024 + h * 256 + wid * 32 + n * 16 + 4 * fq; f32x4 v = accO[m];
;                             if (dir) { const u32x2 old = *(const u32x2*)dst; v[0] += bflo(old.x); v[1] += bfhi(old.x); v[2] += bflo(old.y); v[3] += bfhi(old.y); }
;                             *(u32x2*)dst = (u32x2){cvt_pk_bf16(v[0], v[1]), cvt_pk_bf16(v[2], v[3])}; }
	v_mfma_f32_16x16x32_bf16 v[112:115], v[166:169], v[170:173], v[112:115]
	ds_read_b128 v[166:169], v234 offset:13248
	ds_read_b128 v[170:173], v235
	s_waitcnt lgkmcnt(4)
	v_mfma_f32_16x16x32_bf16 v[100:103], v[84:87], v[88:91], v[100:103]
	ds_read_b128 v[88:91], v235 offset:2304
	s_waitcnt lgkmcnt(4)
	v_mfma_f32_16x16x32_bf16 v[104:107], v[84:87], v[92:95], v[104:107]
	ds_read_b128 v[92:95], v235 offset:4608
	s_waitcnt lgkmcnt(4)
	v_mfma_f32_16x16x32_bf16 v[108:111], v[84:87], v[96:99], v[108:111]
	ds_read_b128 v[96:99], v235 offset:6912
	s_waitcnt lgkmcnt(4)
	v_mfma_f32_16x16x32_bf16 v[112:115], v[84:87], v[166:169], v[112:115]
	ds_read_b128 v[84:87], v235 offset:64
	ds_read_b128 v[166:169], v235 offset:2368
	s_waitcnt lgkmcnt(5)
	v_mfma_f32_16x16x32_bf16 v[100:103], v[176:179], v[170:173], v[100:103]
	ds_read_b128 v[170:173], v235 offset:4672
	s_waitcnt lgkmcnt(5)
	v_mfma_f32_16x16x32_bf16 v[104:107], v[176:179], v[88:91], v[104:107]
	ds_read_b128 v[88:91], v235 offset:6976
	s_waitcnt lgkmcnt(5)
	v_mfma_f32_16x16x32_bf16 v[108:111], v[176:179], v[92:95], v[108:111]
	s_waitcnt lgkmcnt(4)
	v_mfma_f32_16x16x32_bf16 v[112:115], v[176:179], v[96:99], v[112:115]
	s_waitcnt lgkmcnt(3)
	v_mfma_f32_16x16x32_bf16 v[100:103], v[180:183], v[84:87], v[100:103]
	s_waitcnt lgkmcnt(2)
	v_mfma_f32_16x16x32_bf16 v[104:107], v[180:183], v[166:169], v[104:107]
	s_waitcnt lgkmcnt(1)
	v_mfma_f32_16x16x32_bf16 v[108:111], v[180:183], v[170:173], v[108:111]
	s_waitcnt lgkmcnt(0)
	v_mfma_f32_16x16x32_bf16 v[112:115], v[180:183], v[88:91], v[112:115]
	s_nop 7
	s_and_b64 vcc, exec, s[66:67]
	s_cbranch_vccnz .Lgla_s4_skip0
	s_waitcnt vmcnt(0)
	v_lshlrev_b32_e32 v166, 16, v244
	v_and_b32_e32 v167, 0xffff0000, v244
	v_lshlrev_b32_e32 v168, 16, v245
	v_and_b32_e32 v169, 0xffff0000, v245
	v_pk_add_f32 v[100:101], v[100:101], v[166:167]
	v_pk_add_f32 v[102:103], v[102:103], v[168:169]
	v_lshlrev_b32_e32 v166, 16, v246
	v_and_b32_e32 v167, 0xffff0000, v246
	v_lshlrev_b32_e32 v168, 16, v247
	v_and_b32_e32 v169, 0xffff0000, v247
	v_pk_add_f32 v[104:105], v[104:105], v[166:167]
	v_pk_add_f32 v[106:107], v[106:107], v[168:169]
	v_lshlrev_b32_e32 v166, 16, v250
	v_and_b32_e32 v167, 0xffff0000, v250
	v_lshlrev_b32_e32 v168, 16, v251
	v_and_b32_e32 v169, 0xffff0000, v251
	v_pk_add_f32 v[108:109], v[108:109], v[166:167]
	v_pk_add_f32 v[110:111], v[110:111], v[168:169]
	v_lshlrev_b32_e32 v166, 16, v252
	v_and_b32_e32 v167, 0xffff0000, v252
	v_lshlrev_b32_e32 v168, 16, v253
	v_and_b32_e32 v169, 0xffff0000, v253
	v_pk_add_f32 v[112:113], v[112:113], v[166:167]
	v_pk_add_f32 v[114:115], v[114:115], v[168:169]
	global_load_dwordx2 v[244:245], v153, s[4:5] offset:32
	s_add_u32 s4, s4, 0x8000
	s_addc_u32 s5, s5, 0
	global_load_dwordx2 v[246:247], v153, s[4:5] offset:32
	s_add_u32 s4, s4, 0x8000
	s_addc_u32 s5, s5, 0
	global_load_dwordx2 v[250:251], v153, s[4:5] offset:32
	s_add_u32 s4, s4, 0x8000
	s_addc_u32 s5, s5, 0
	global_load_dwordx2 v[252:253], v153, s[4:5] offset:32
	s_sub_u32 s4, s4, 0x18000
	s_subb_u32 s5, s5, 0
; #define LAS __attribute__((address_space(3)))
; __device__ __forceinline__ unsigned cvt_pk_bf16(float lo, float hi) { const f32x2 v = {lo, hi}; const bf16x2_t b = __builtin_convertvector(v, bf16x2_t); return __builtin_bit_cast(unsigned, b); }
; __device__ __forceinline__ float bflo(unsigned w) { return __uint_as_float(w << 16); }
; __device__ __forceinline__ float bfhi(unsigned w) { return __uint_as_float(w & 0xffff0000u); }
; #define MFMA16(a, b, c) __builtin_amdgcn_mfma_f32_16x16x32_bf16((a), (b), (c), 0, 0, 0)
; template <bool PASS2>
; __device__ __forceinline__ void gla_pass(LAS unsigned char* lds, const Params& p, int layer) {
;     ...
;                 for (int it = 0; it < 4; ++it) { const int pi = tid + 512 * it, row = pi >> 5, seg = pi & 31;
;                     rv[it] = *(const u32x4*)(P + (size_t)(t0 + row) * PW + 1024 + h * 256 + seg * 8); }
;     ...
;                         for (int kb = 0; kb < 4; ++kb) { const bf16x8 A = *(LAS bf16x8*)(lds + SST + (wid * 32 + n * 16 + fr) * 272 + (kb * 32 + fq * 8) * 2);
; #pragma unroll
;                             for (int m = 0; m < 4; ++m) { const bf16x8 B = *(LAS bf16x8*)(lds + SQ + (m * 16 + fr) * 272 + (kb * 32 + fq * 8) * 2); accO[m] = MFMA16(A, B, accO[m]); } }
; #pragma unroll
;                         for (int kb2 = 0; kb2 < 2; ++kb2)
; #pragma unroll
;                             for (int m = 0; m < 4; ++m) { const bf16x8 B = *(LAS bf16x8*)(lds + SP + (m * 16 + fr) * 144 + (kb2 * 32 + fq * 8) * 2); accO[m] = MFMA16(vf[n][kb2], B, accO[m]); }
; #pragma unroll
;                         for (int m = 0; m < 4; ++m) { bf16_t* dst = O + (size_t)(t0 + m * 16 + fr) * 1024 + h * 256 + wid * 32 + n * 16 + 4 * fq; f32x4 v = accO[m];
;                             if (dir) { const u32x2 old = *(const u32x2*)dst; v[0] += bflo(old.x); v[1] += bfhi(old.x); v[2] += bflo(old.y); v[3] += bfhi(old.y); }
;                             *(u32x2*)dst = (u32x2){cvt_pk_bf16(v[0], v[1]), cvt_pk_bf16(v[2], v[3])}; }
;                         asm volatile("" ::: "memory");
;                     }
;                 }
;                 if (cc < 7) GLA_ISSUE(cc + 1);
.Lgla_s4_skip0:
	v_cvt_pk_bf16_f32 v100, v100, v101
	v_cvt_pk_bf16_f32 v101, v102, v103
	global_store_dwordx2 v153, v[100:101], s[4:5]
	s_add_u32 s4, s4, 0x8000
	s_addc_u32 s5, s5, 0
	v_cvt_pk_bf16_f32 v104, v104, v105
	v_cvt_pk_bf16_f32 v105, v106, v107
	global_store_dwordx2 v153, v[104:105], s[4:5]
	s_add_u32 s4, s4, 0x8000
	s_addc_u32 s5, s5, 0
	v_cvt_pk_bf16_f32 v108, v108, v109
	v_cvt_pk_bf16_f32 v109, v110, v111
	global_store_dwordx2 v153, v[108:109], s[4:5]
	s_add_u32 s4, s4, 0x8000
	s_addc_u32 s5, s5, 0
	v_cvt_pk_bf16_f32 v112, v112, v113
	v_cvt_pk_bf16_f32 v113, v114, v115
	global_store_dwordx2 v153, v[112:113], s[4:5]
	s_sub_u32 s4, s4, 0x18000
	s_subb_u32 s5, s5, 0
	ds_read_b128 v[84:87], v231
	ds_read_b128 v[88:91], v234
	ds_read_b128 v[92:95], v234 offset:4352
	ds_read_b128 v[96:99], v234 offset:8704
	ds_read_b128 v[166:169], v234 offset:13056
	ds_read_b128 v[170:173], v231 offset:64
	s_waitcnt lgkmcnt(4)
	v_mfma_f32_16x16x32_bf16 v[100:103], v[84:87], v[88:91], 0
	ds_read_b128 v[88:91], v234 offset:64
	s_waitcnt lgkmcnt(4)
	v_mfma_f32_16x16x32_bf16 v[104:107], v[84:87], v[92:95], 0
	ds_read_b128 v[92:95], v234 offset:4416
	s_waitcnt lgkmcnt(4)
	v_mfma_f32_16x16x32_bf16 v[108:111], v[84:87], v[96:99], 0
	ds_read_b128 v[96:99], v234 offset:8768
	s_waitcnt lgkmcnt(4)
	v_mfma_f32_16x16x32_bf16 v[112:115], v[84:87], v[166:169], 0
	ds_read_b128 v[84:87], v234 offset:13120
	ds_read_b128 v[166:169], v231 offset:128
	s_waitcnt lgkmcnt(4)
	v_mfma_f32_16x16x32_bf16 v[100:103], v[170:173], v[88:91], v[100:103]
	ds_read_b128 v[88:91], v234 offset:128
	s_waitcnt lgkmcnt(4)
	v_mfma_f32_16x16x32_bf16 v[104:107], v[170:173], v[92:95], v[104:107]
	ds_read_b128 v[92:95], v234 offset:4480
	s_waitcnt lgkmcnt(4)
	v_mfma_f32_16x16x32_bf16 v[108:111], v[170:173], v[96:99], v[108:111]
	ds_read_b128 v[96:99], v234 offset:8832
	s_waitcnt lgkmcnt(4)
	v_mfma_f32_16x16x32_bf16 v[112:115], v[170:173], v[84:87], v[112:115]
	ds_read_b128 v[170:173], v234 offset:13184
	ds_read_b128 v[84:87], v231 offset:192
	s_waitcnt lgkmcnt(4)
	v_mfma_f32_16x16x32_bf16 v[100:103], v[166:169], v[88:91], v[100:103]
	ds_read_b128 v[88:91], v234 offset:192
	s_waitcnt lgkmcnt(4)
	v_mfma_f32_16x16x32_bf16 v[104:107], v[166:169], v[92:95], v[104:107]
	ds_read_b128 v[92:95], v234 offset:4544
	s_waitcnt lgkmcnt(4)
	v_mfma_f32_16x16x32_bf16 v[108:111], v[166:169], v[96:99], v[108:111]
	ds_read_b128 v[96:99], v234 offset:8896
	s_waitcnt lgkmcnt(4)
	v_mfma_f32_16x16x32_bf16 v[112:115], v[166:169], v[170:173], v[112:115]
	ds_read_b128 v[166:169], v234 offset:13248
	ds_read_b128 v[170:173], v235
	s_waitcnt lgkmcnt(4)
	v_mfma_f32_16x16x32_bf16 v[100:103], v[84:87], v[88:91], v[100:103]
	ds_read_b128 v[88:91], v235 offset:2304
	s_waitcnt lgkmcnt(4)
	v_mfma_f32_16x16x32_bf16 v[104:107], v[84:87], v[92:95], v[104:107]
	ds_read_b128 v[92:95], v235 offset:4608
	s_waitcnt lgkmcnt(4)
	v_mfma_f32_16x16x32_bf16 v[108:111], v[84:87], v[96:99], v[108:111]
	ds_read_b128 v[96:99], v235 offset:6912
	s_waitcnt lgkmcnt(4)
	v_mfma_f32_16x16x32_bf16 v[112:115], v[84:87], v[166:169], v[112:115]
	ds_read_b128 v[84:87], v235 offset:64
	ds_read_b128 v[166:169], v235 offset:2368
	s_waitcnt lgkmcnt(5)
	v_mfma_f32_16x16x32_bf16 v[100:103], v[236:239], v[170:173], v[100:103]
	ds_read_b128 v[170:173], v235 offset:4672
	s_waitcnt lgkmcnt(5)
	v_mfma_f32_16x16x32_bf16 v[104:107], v[236:239], v[88:91], v[104:107]
	ds_read_b128 v[88:91], v235 offset:6976
	s_waitcnt lgkmcnt(5)
	v_mfma_f32_16x16x32_bf16 v[108:111], v[236:239], v[92:95], v[108:111]
	s_waitcnt lgkmcnt(4)
	v_mfma_f32_16x16x32_bf16 v[112:115], v[236:239], v[96:99], v[112:115]
	s_waitcnt lgkmcnt(3)
	v_mfma_f32_16x16x32_bf16 v[100:103], v[240:243], v[84:87], v[100:103]
	s_waitcnt lgkmcnt(2)
	v_mfma_f32_16x16x32_bf16 v[104:107], v[240:243], v[166:169], v[104:107]
	s_waitcnt lgkmcnt(1)
	v_mfma_f32_16x16x32_bf16 v[108:111], v[240:243], v[170:173], v[108:111]
	s_waitcnt lgkmcnt(0)
	v_mfma_f32_16x16x32_bf16 v[112:115], v[240:243], v[88:91], v[112:115]
	s_nop 7
	s_and_b64 vcc, exec, s[66:67]
	s_cbranch_vccnz .Lgla_s4_skip1
	s_waitcnt vmcnt(4)
	v_lshlrev_b32_e32 v166, 16, v244
	v_and_b32_e32 v167, 0xffff0000, v244
	v_lshlrev_b32_e32 v168, 16, v245
	v_and_b32_e32 v169, 0xffff0000, v245
	v_pk_add_f32 v[100:101], v[100:101], v[166:167]
	v_pk_add_f32 v[102:103], v[102:103], v[168:169]
	v_lshlrev_b32_e32 v166, 16, v246
	v_and_b32_e32 v167, 0xffff0000, v246
	v_lshlrev_b32_e32 v168, 16, v247
	v_and_b32_e32 v169, 0xffff0000, v247
	v_pk_add_f32 v[104:105], v[104:105], v[166:167]
	v_pk_add_f32 v[106:107], v[106:107], v[168:169]
	v_lshlrev_b32_e32 v166, 16, v250
	v_and_b32_e32 v167, 0xffff0000, v250
	v_lshlrev_b32_e32 v168, 16, v251
	v_and_b32_e32 v169, 0xffff0000, v251
	v_pk_add_f32 v[108:109], v[108:109], v[166:167]
	v_pk_add_f32 v[110:111], v[110:111], v[168:169]
	v_lshlrev_b32_e32 v166, 16, v252
	v_and_b32_e32 v167, 0xffff0000, v252
	v_lshlrev_b32_e32 v168, 16, v253
	v_and_b32_e32 v169, 0xffff0000, v253
	v_pk_add_f32 v[112:113], v[112:113], v[166:167]
	v_pk_add_f32 v[114:115], v[114:115], v[168:169]
.Lgla_s4_skip1:
	v_cvt_pk_bf16_f32 v100, v100, v101
	v_cvt_pk_bf16_f32 v101, v102, v103
	global_store_dwordx2 v153, v[100:101], s[4:5] offset:32
	s_add_u32 s4, s4, 0x8000
	s_addc_u32 s5, s5, 0
	v_cvt_pk_bf16_f32 v104, v104, v105
	v_cvt_pk_bf16_f32 v105, v106, v107
	global_store_dwordx2 v153, v[104:105], s[4:5] offset:32
	s_add_u32 s4, s4, 0x8000
	s_addc_u32 s5, s5, 0
	v_cvt_pk_bf16_f32 v108, v108, v109
	v_cvt_pk_bf16_f32 v109, v110, v111
	global_store_dwordx2 v153, v[108:109], s[4:5] offset:32
	s_add_u32 s4, s4, 0x8000
	s_addc_u32 s5, s5, 0
	v_cvt_pk_bf16_f32 v112, v112, v113
	v_cvt_pk_bf16_f32 v113, v114, v115
	global_store_dwordx2 v153, v[112:113], s[4:5] offset:32
	s_cmp_eq_u32 s68, 7
	s_cbranch_scc1 .LBB0_514
	s_sub_i32 s66, 6, s68
	s_add_i32 s68, s68, 1
	s_and_b64 s[4:5], s[14:15], exec
	s_cselect_b32 s4, s68, s66
	s_lshl_b32 s66, s4, 6
	s_add_i32 s66, s66, s97
	v_add_u32_e32 v166, s66, v189
	v_add_u32_e32 v170, s66, v190
	v_mad_i64_i32 v[166:167], s[4:5], v166, s80, v[140:141]
	v_mad_i64_i32 v[170:171], s[4:5], v170, s80, v[140:141]
	global_load_dwordx4 v[104:107], v[166:167], off
	global_load_dwordx4 v[100:103], v[170:171], off
	v_add_u32_e32 v84, s66, v193
	v_add_u32_e32 v86, s66, v194
	v_add_u32_e32 v92, s66, v195
	v_add_u32_e32 v94, s66, v196
	v_mad_i64_i32 v[84:85], s[4:5], v84, s80, v[160:161]
	v_mad_i64_i32 v[88:89], s[4:5], v86, s80, v[160:161]
	v_mad_i64_i32 v[92:93], s[4:5], v92, s80, v[160:161]
	v_mad_i64_i32 v[96:97], s[4:5], v94, s80, v[160:161]
	global_load_dwordx4 v[84:87], v[84:85], off offset:2048
	s_nop 0
	global_load_dwordx4 v[88:91], v[88:89], off offset:2048
	s_nop 0
	global_load_dwordx4 v[92:95], v[92:93], off offset:2048
	s_nop 0
	global_load_dwordx4 v[96:99], v[96:97], off offset:2048
	s_branch .LBB0_452
